# prep phase hand-written (GQA head RMS-norm+rope, MLA latent norms, rope key): wave reductions by DPP+readlane instead of LDS bpermute chains, ten independent reductions per row, row pair per wave
# speedup vs baseline: 1.0106x; 1.0049x over previous
; DI int get_tid() { int t = threadIdx.x; asm volatile("" : "+v"(t)); return t; }
; DI void prep_rows(const Params& p, int layer) {
;   const int lane = get_tid() & 63, gw = blockIdx.x * 4 + (get_tid() >> 6), nw = gridDim.x * 4;
;   const bf16_t* U = (const bf16_t*)(p.ws + OFF_U);
;   const float gq = p.gqa_q_g[layer * 64 + lane], gk = p.gqa_k_g[layer * 64 + lane];
;   const float4 g4 = *(const float4*)(p.mla_q_g + layer * 256 + lane * 4);
;   const float2 g2 = *(const float2*)(p.mla_kv_g + layer * 128 + lane * 2);
; DI void xcd_barrier(const XcdBarrier& b) {
;   asm volatile("s_waitcnt vmcnt(0)" ::: "memory");
;   __syncthreads();
;   if (threadIdx.x == 0) {
;     unsigned* bar = b.bar;
;     __builtin_amdgcn_s_waitcnt(0);
;     unsigned nloc = b.st[0], nx = b.st[1];
;     if (nloc == 0u) { xcd_barrier_complete(bar, b.x, nloc, nx); b.st[0] = nloc; b.st[1] = nx; }
.LBB0_506:
	s_or_b64 exec, exec, s[0:1]
	v_mov_b32_e32 v6, v143
	s_waitcnt lgkmcnt(0)
	v_mov_b32_e32 v0, v143
	s_barrier
	s_movk_i32 s0, 0x4400
	v_ashrrev_i32_e32 v16, 6, v0
	v_add_u32_e32 v40, s31, v16
	v_cmp_gt_i32_e32 vcc, s0, v40
	s_and_saveexec_b64 s[6:7], vcc
	s_cbranch_execz .LBB0_517
	v_and_b32_e32 v18, 63, v6
	v_lshl_or_b32 v0, s52, 6, v18
	v_mov_b32_e32 v1, v141
	v_readlane_b32 s36, v236, 5
	s_lshl_b32 s0, s52, 8
	s_mov_b32 s1, s92
	v_lshlrev_b64 v[0:1], 2, v[0:1]
	v_readlane_b32 s40, v236, 9
	v_readlane_b32 s41, v236, 10
	v_readlane_b32 s42, v236, 11
	v_readlane_b32 s43, v236, 12
	v_readlane_b32 s44, v236, 13
	s_lshl_b64 s[0:1], s[0:1], 2
	v_readlane_b32 s45, v236, 14
	v_lshl_add_u64 v[2:3], s[40:41], 0, v[0:1]
	v_lshl_add_u64 v[0:1], s[42:43], 0, v[0:1]
	s_add_u32 s0, s44, s0
	global_load_dword v42, v[0:1], off
	s_addc_u32 s1, s45, s1
	v_lshlrev_b32_e32 v0, 4, v18
	global_load_dword v41, v[2:3], off
	v_readlane_b32 s46, v236, 15
	global_load_dwordx4 v[0:3], v0, s[0:1]
	s_lshl_b32 s0, s52, 7
	s_mov_b32 s1, s92
	s_lshl_b64 s[0:1], s[0:1], 2
	v_readlane_b32 s47, v236, 16
	s_add_u32 s0, s46, s0
	s_addc_u32 s1, s47, s1
	v_lshlrev_b32_e32 v10, 3, v18
	global_load_dwordx2 v[4:5], v10, s[0:1]
	v_readlane_b32 s38, v236, 7
	v_readlane_b32 s39, v236, 8
	v_and_b32_e32 v7, 16, v6
	v_cmp_lt_i32_e64 s[0:1], v202, v196
	v_cmp_eq_u32_e64 s[38:39], 0, v7
	v_lshlrev_b32_e32 v22, 1, v18
	v_cndmask_b32_e64 v7, v195, v202, s[0:1]
	v_cmp_lt_i32_e64 s[0:1], v201, v196
	v_lshlrev_b32_e32 v43, 2, v7
	v_mov_b32_e32 v23, v141
	v_cndmask_b32_e64 v7, v195, v201, s[0:1]
	v_cmp_lt_i32_e64 s[0:1], v200, v196
	v_lshlrev_b32_e32 v44, 2, v7
	v_and_b32_e32 v24, 31, v6
	v_cndmask_b32_e64 v7, v195, v200, s[0:1]
	v_cmp_lt_i32_e64 s[0:1], v199, v196
	v_lshlrev_b32_e32 v45, 2, v7
	v_and_b32_e32 v17, 15, v6
	v_cndmask_b32_e64 v7, v195, v199, s[0:1]
	v_cmp_lt_i32_e64 s[0:1], v198, v196
	v_lshlrev_b32_e32 v46, 2, v7
	v_and_b32_e32 v19, 7, v6
	v_cndmask_b32_e64 v7, v195, v198, s[0:1]
	v_cmp_lt_i32_e64 s[0:1], v197, v196
	v_lshlrev_b32_e32 v47, 2, v7
	v_mov_b32_e32 v11, v141
	v_cndmask_b32_e64 v7, v195, v197, s[0:1]
	v_readlane_b32 s0, v235, 36
	v_lshlrev_b32_e32 v48, 2, v7
	v_and_b32_e32 v7, 8, v6
	v_bfe_u32 v6, v6, 5, 1
	v_readlane_b32 s1, v235, 37
	v_cmp_eq_u32_e64 s[40:41], 0, v7
	v_mul_u32_u24_e32 v49, 3, v6
	v_lshl_add_u64 v[6:7], s[0:1], 0, v[22:23]
	v_readlane_b32 s0, v235, 38
	v_readlane_b32 s1, v235, 39
	v_lshlrev_b32_e32 v20, 2, v18
	v_mov_b32_e32 v21, v141
	v_lshl_add_u64 v[8:9], s[0:1], 0, v[22:23]
	v_readlane_b32 s0, v235, 42
	v_readlane_b32 s1, v235, 43
	v_lshlrev_b32_e32 v14, 1, v24
	v_mov_b32_e32 v15, v141
	v_lshl_add_u64 v[10:11], s[0:1], 0, v[10:11]
	v_readlane_b32 s0, v235, 40
	v_readlane_b32 s1, v235, 41
	v_readlane_b32 s37, v236, 6
	v_cmp_gt_u32_e32 vcc, 32, v18
	v_lshl_add_u64 v[12:13], s[0:1], 0, v[20:21]
	v_readlane_b32 s0, v235, 44
	v_readlane_b32 s1, v235, 45
	v_cmp_gt_u32_e64 s[36:37], 16, v24
	s_mov_b64 s[10:11], 0
	v_lshl_add_u64 v[14:15], s[0:1], 0, v[14:15]
	v_readlane_b32 s0, v234, 14
	v_lshlrev_b32_e32 v50, 3, v17
	v_lshlrev_b32_e32 v51, 3, v19
	v_lshl_add_u32 v16, v16, 1, s0
	v_lshlrev_b32_e32 v140, 1, v18
	v_lshlrev_b32_e32 v18, 1, v20
	v_lshlrev_b32_e32 v20, 1, v22
	v_lshlrev_b32_e32 v22, 1, v24
	v_readlane_b32 s48, v236, 17
	v_readlane_b32 s49, v236, 18
	v_readlane_b32 s50, v236, 19
	v_readlane_b32 s51, v236, 20
	s_mov_b32 s101, s52
	s_branch .Lpp_entry
.Lpp_ret:
.LBB0_517:
	s_or_b64 exec, exec, s[6:7]
	s_waitcnt vmcnt(0)
	s_barrier
	s_mov_b64 s[0:1], exec
	v_readlane_b32 s6, v236, 2
	v_readlane_b32 s7, v236, 3
	s_and_b64 s[6:7], s[0:1], s[6:7]
	s_mov_b64 exec, s[6:7]
	s_cbranch_execz .LBB0_565
	s_waitcnt vmcnt(0) expcnt(0) lgkmcnt(0)
	ds_read_b32 v2, v188
	ds_read_b32 v0, v189
	s_waitcnt lgkmcnt(1)
	v_cmp_ne_u32_e32 vcc, 0, v2
	s_cbranch_vccnz .LBB0_533
	s_mov_b32 s28, 1
	s_branch .LBB0_521

; DI int get_tid() { int t = threadIdx.x; asm volatile("" : "+v"(t)); return t; }
; DI void prep_row_load(const Params& p, int row, const bf16_t* ur, int lane, PrepRow& R) {
;   {
;     const float2* csg = (const float2*)(p.ws + OFF_ROPEG);
;     const float2* csm = (const float2*)(p.ws + OFF_ROPEM);
;     const int s = row & 4095, d = lane & 31;
;     const int pg = (lane >> 5) ? (s & 63) : (s >> 6), pm = (d >> 4) ? (s & 63) : (s >> 6);
;     R.cs = csg[pg * 16 + (lane & 15)];
;     R.tm = csm[pm * 8 + (d & 7)];
;     if (row >= NLAT) { R.cs = make_float2(1.f, 0.f); R.tm = make_float2(1.f, 0.f); }
;   }
; #pragma unroll
;   for (int hd = 0; hd < 8; ++hd) R.hv[hd] = ur[768 + hd * 64 + lane];
;   R.mq = *(const uint2*)(ur + 1408 + lane * 4);
;   R.mkv = *(const unsigned*)(ur + 1664 + lane * 2);
;   R.kr = ur[1792 + (lane & 31)];
; }
; DI void prep_rows(const Params& p, int layer) {
;   const int lane = get_tid() & 63, gw = blockIdx.x * 4 + (get_tid() >> 6), nw = gridDim.x * 4;
;   const bf16_t* U = (const bf16_t*)(p.ws + OFF_U);
;   const float gq = p.gqa_q_g[layer * 64 + lane], gk = p.gqa_k_g[layer * 64 + lane];
;   const float4 g4 = *(const float4*)(p.mla_q_g + layer * 256 + lane * 4);
;   const float2 g2 = *(const float2*)(p.mla_kv_g + layer * 128 + lane * 2);
;   for (int pr = gw; pr < (NTOK >> 1); pr += nw) {
;     const int row = pr * 2;
;     PrepRow Ra, Rb;
;     prep_row_load(p, row, U + (size_t)row * INP, lane, Ra);
;     prep_row_load(p, row + 1, U + (size_t)(row + 1) * INP, lane, Rb);
.Lpp_entry:
	v_writelane_b32 v254, s52, 0
	v_writelane_b32 v254, s53, 1
	v_writelane_b32 v254, s54, 2
	v_writelane_b32 v254, s55, 3
	v_writelane_b32 v254, s56, 4
	v_writelane_b32 v254, s57, 5
	v_writelane_b32 v254, s58, 6
	v_writelane_b32 v254, s59, 7
	v_writelane_b32 v254, s60, 8
	v_writelane_b32 v254, s61, 9
	v_writelane_b32 v254, s62, 10
	v_writelane_b32 v254, s63, 11
	v_writelane_b32 v254, s64, 12
	v_writelane_b32 v254, s65, 13
	v_writelane_b32 v254, s66, 14
	v_writelane_b32 v254, s67, 15
	v_writelane_b32 v254, s68, 16
	v_writelane_b32 v254, s69, 17
	v_writelane_b32 v254, s70, 18
	v_writelane_b32 v254, s71, 19
	v_writelane_b32 v254, s72, 20
	v_writelane_b32 v254, s73, 21
	v_writelane_b32 v254, s74, 22
	v_writelane_b32 v254, s75, 23
	v_writelane_b32 v254, s76, 24
	v_writelane_b32 v254, s77, 25
	v_writelane_b32 v254, s78, 26
	v_writelane_b32 v254, s79, 27
	v_writelane_b32 v254, s80, 28
	v_writelane_b32 v254, s81, 29
	v_writelane_b32 v254, s82, 30
	v_writelane_b32 v254, s83, 31
	v_writelane_b32 v254, s84, 32
	v_writelane_b32 v254, s85, 33
	v_writelane_b32 v254, s86, 34
	v_writelane_b32 v254, s87, 35
	v_writelane_b32 v254, s88, 36
	v_writelane_b32 v254, s89, 37
	v_writelane_b32 v254, s90, 38
	v_writelane_b32 v254, s91, 39
	s_mov_b32 s52, s101
	v_lshrrev_b32_e32 v32, 6, v143
	v_readlane_b32 s0, v255, 0
	s_nop 0
	v_readfirstlane_b32 s1, v32
	s_nop 3
	s_lshl_b32 s53, s0, 2
	s_add_u32 s53, s53, s1
	s_lshl_b32 s54, s26, 2
	v_readlane_b32 s56, v255, 1
	v_readlane_b32 s57, v255, 2
	s_nop 3
	s_load_dwordx2 s[10:11], s[56:57], 0x90
	s_load_dwordx2 s[12:13], s[56:57], 0x98
	s_load_dwordx2 s[28:29], s[56:57], 0xa0
	s_load_dwordx2 s[44:45], s[56:57], 0xa8
	v_and_b32_e32 v33, 63, v143
	v_lshl_add_u32 v34, s52, 6, v33
	v_lshlrev_b32_e32 v34, 2, v34
	v_lshlrev_b32_e32 v35, 4, v33
	s_lshl_b32 s0, s52, 10
	v_add_u32_e32 v35, s0, v35
	v_lshlrev_b32_e32 v36, 3, v33
	s_lshl_b32 s0, s52, 9
	v_add_u32_e32 v36, s0, v36
	s_waitcnt lgkmcnt(0)
	global_load_dword v144, v34, s[10:11]
	global_load_dword v145, v34, s[12:13]
	global_load_dwordx4 v[146:149], v35, s[28:29]
	global_load_dwordx2 v[150:151], v36, s[44:45]
	v_lshlrev_b32_e32 v152, 1, v33
	v_lshlrev_b32_e32 v153, 3, v33
	v_lshlrev_b32_e32 v154, 2, v33
	v_and_b32_e32 v37, 31, v33
	v_lshlrev_b32_e32 v155, 1, v37
	v_and_b32_e32 v38, 16, v33
	v_sub_u32_e32 v38, 16, v38
	v_lshlrev_b32_e32 v156, 27, v38
	v_and_b32_e32 v38, 8, v33
	v_sub_u32_e32 v38, 8, v38
	v_lshlrev_b32_e32 v157, 28, v38
	v_and_b32_e32 v38, 15, v33
	v_lshlrev_b32_e32 v158, 3, v38
	v_and_b32_e32 v38, 7, v33
	v_lshlrev_b32_e32 v159, 3, v38
	v_lshrrev_b32_e32 v163, 5, v33
	v_bfe_u32 v164, v33, 4, 1
	v_mul_u32_u24_e32 v38, 3, v163
	s_mov_b32 s0, 0xcc000
	v_mul_lo_u32 v38, v38, s0
	v_add_u32_e32 v160, v38, v155
	v_add_u32_e32 v160, 0x80, v160
	v_mov_b32_e32 v161, 0x358637bd
	v_mov_b32_e32 v162, 0x3e38aa3b
	v_mov_b32_e32 v165, 1.0
	s_waitcnt vmcnt(0)
	s_add_u32 s28, s24, 0x1e8d4000
	s_addc_u32 s29, s25, 0
	s_add_u32 s44, s24, 0x1e8d6000
	s_addc_u32 s45, s25, 0
.Lpp_loop_1:
	s_cmpk_ge_u32 s53, 0x4400
	s_cbranch_scc1 .Lpp_done_2
	s_lshl_b32 s70, s53, 1
	s_mul_i32 s0, s70, 3840
	s_add_u32 s58, s24, s0
	s_addc_u32 s59, s25, 0
	global_load_ushort v0, v152, s[58:59] offset:1536
	global_load_ushort v1, v152, s[58:59] offset:1664
	global_load_ushort v2, v152, s[58:59] offset:1792
	global_load_ushort v3, v152, s[58:59] offset:1920
	global_load_ushort v4, v152, s[58:59] offset:2048
	global_load_ushort v5, v152, s[58:59] offset:2176
	global_load_ushort v6, v152, s[58:59] offset:2304
	global_load_ushort v7, v152, s[58:59] offset:2432
	global_load_dwordx2 v[8:9], v153, s[58:59] offset:2816
	global_load_dword v14, v154, s[58:59] offset:3328
	global_load_ushort v17, v155, s[58:59] offset:3584
	s_cmp_lt_u32 s70, 0x8000
	s_cselect_b32 s71, 1, 0
	s_cbranch_scc0 .Lpp_ctx_3
	s_lshr_b32 s0, s70, 12
	s_and_b32 s1, s70, 0xfff
	s_add_u32 s10, s1, 256
	s_lshr_b32 s11, s1, 6
	s_and_b32 s12, s1, 63
	s_sub_u32 s12, s12, s11
	v_mov_b32_e32 v32, s12
	v_mul_lo_u32 v36, v32, v163
	v_add_u32_e32 v36, s11, v36
	v_lshl_add_u32 v36, v36, 7, v158
	v_mul_lo_u32 v37, v32, v164
	v_add_u32_e32 v37, s11, v37
	v_lshl_add_u32 v37, v37, 6, v159
	global_load_dwordx2 v[18:19], v36, s[28:29]
	global_load_dwordx2 v[20:21], v37, s[44:45]
	s_branch .Lpp_j_4
.Lpp_ctx_3:
	s_sub_u32 s1, s70, 0x8000
	s_lshr_b32 s0, s1, 8
	s_and_b32 s10, s1, 255
	v_mov_b32_e32 v18, 1.0
	v_mov_b32_e32 v19, 0
	v_mov_b32_e32 v20, 1.0
	v_mov_b32_e32 v21, 0
	global_load_dword v36, v154, s[58:59] offset:3328
	global_load_dword v37, v154, s[58:59] offset:3328
.Lpp_j_4:
	s_mul_i32 s11, s0, 26112
	s_add_u32 s11, s11, s10
	s_lshl_b32 s12, s11, 7
	s_add_u32 s12, s12, 0x7f80000
	s_add_u32 s60, s24, s12
	s_addc_u32 s61, s25, 0
	s_mul_i32 s12, s11, 192
	s_add_u32 s12, s12, 0xd040000
	s_add_u32 s68, s24, s12
	s_addc_u32 s69, s25, 0
	s_mul_i32 s11, s0, 8704
	s_add_u32 s11, s11, s10
	s_lshl_b32 s12, s11, 7
	s_add_u32 s12, s12, 0x9900000
	s_add_u32 s62, s24, s12
	s_addc_u32 s63, s25, 0
	s_lshl_b32 s12, s70, 9
	s_add_u32 s12, s12, 0x11000000
	s_add_u32 s64, s24, s12
	s_addc_u32 s65, s25, 0
	s_lshl_b32 s12, s70, 8
	s_add_u32 s12, s12, 0x12100000
	s_add_u32 s66, s24, s12
	s_addc_u32 s67, s25, 0
	s_lshl_b32 s86, s53, 1
	s_add_u32 s86, s86, 1
	s_mul_i32 s0, s86, 3840
	s_add_u32 s74, s24, s0
	s_addc_u32 s75, s25, 0
	global_load_ushort v40, v152, s[74:75] offset:1536
	global_load_ushort v41, v152, s[74:75] offset:1664
	global_load_ushort v42, v152, s[74:75] offset:1792
	global_load_ushort v43, v152, s[74:75] offset:1920
	global_load_ushort v44, v152, s[74:75] offset:2048
	global_load_ushort v45, v152, s[74:75] offset:2176
	global_load_ushort v46, v152, s[74:75] offset:2304
	global_load_ushort v47, v152, s[74:75] offset:2432
	global_load_dwordx2 v[48:49], v153, s[74:75] offset:2816
	global_load_dword v54, v154, s[74:75] offset:3328
	global_load_ushort v57, v155, s[74:75] offset:3584
	s_cmp_lt_u32 s86, 0x8000
	s_cselect_b32 s87, 1, 0
	s_cbranch_scc0 .Lpp_ctx_5
	s_lshr_b32 s0, s86, 12
	s_and_b32 s1, s86, 0xfff
	s_add_u32 s10, s1, 256
	s_lshr_b32 s11, s1, 6
	s_and_b32 s12, s1, 63
	s_sub_u32 s12, s12, s11
	v_mov_b32_e32 v72, s12
	v_mul_lo_u32 v76, v72, v163
	v_add_u32_e32 v76, s11, v76
	v_lshl_add_u32 v76, v76, 7, v158
	v_mul_lo_u32 v77, v72, v164
	v_add_u32_e32 v77, s11, v77
	v_lshl_add_u32 v77, v77, 6, v159
	global_load_dwordx2 v[58:59], v76, s[28:29]
	global_load_dwordx2 v[60:61], v77, s[44:45]
	s_branch .Lpp_j_6
; DI unsigned pack2(float lo, float hi) { f32x2_t v = {lo, hi}; bf16x2_t r = __builtin_convertvector(v, bf16x2_t); return __builtin_bit_cast(unsigned, r); }
; DI bf16_t f2bf(float x) { return (bf16_t)(pack2(x, x) & 0xffffu); }
; DI float bf2f(bf16_t v) { return __uint_as_float(((unsigned)v) << 16); }
; DI void prep_row_store(const Params& p, int layer, int row, int lane, const PrepRow& R, float gq, float gk, float4 g4, float2 g2) {
;     ...
;   for (int hd = 0; hd < 8; ++hd) {
;     float xv = bf2f(R.hv[hd]);
;     float ss = wave_sum(xv * xv);
;     float y = xv * rsqrtf(ss * (1.0f / 64.f) + 1e-6f) * (hd < 6 ? gq : gk);
;     float pv = __shfl_xor(y, 16);
;     float o = y * cs_c + (upper ? pv : -pv) * cs_s;
;     if (hd < 6) Qg[((size_t)(b * 6 + hd) * NKEY + kp) * 64 + lane] = f2bf(o * qs);
;     else Kg[((size_t)(b * 2 + (hd - 6)) * NKEY + kp) * 64 + lane] = f2bf(o);
;   }
;   {
;     const uint2 w = R.mq;
;     float x0 = bf2f((bf16_t)(w.x & 0xffff)), x1 = bf2f((bf16_t)(w.x >> 16)), x2 = bf2f((bf16_t)(w.y & 0xffff)), x3 = bf2f((bf16_t)(w.y >> 16));
;     float ss = wave_sum(x0 * x0 + x1 * x1 + x2 * x2 + x3 * x3);
;     float rstd = rsqrtf(ss * (1.0f / 256.f) + 1e-6f);
;     uint2 o; o.x = pack2(x0 * rstd * g4.x, x1 * rstd * g4.y); o.y = pack2(x2 * rstd * g4.z, x3 * rstd * g4.w);
;     *(uint2*)(MQN + (size_t)row * 256 + lane * 4) = o;
;   }
;   {
;     const unsigned w = R.mkv;
;     float x0 = bf2f((bf16_t)(w & 0xffff)), x1 = bf2f((bf16_t)(w >> 16));
;     float ss = wave_sum(x0 * x0 + x1 * x1);
.Lpp_ctx_5:
	s_sub_u32 s1, s86, 0x8000
	s_lshr_b32 s0, s1, 8
	s_and_b32 s10, s1, 255
	v_mov_b32_e32 v58, 1.0
	v_mov_b32_e32 v59, 0
	v_mov_b32_e32 v60, 1.0
	v_mov_b32_e32 v61, 0
	global_load_dword v76, v154, s[74:75] offset:3328
	global_load_dword v77, v154, s[74:75] offset:3328
.Lpp_j_6:
	s_mul_i32 s11, s0, 26112
	s_add_u32 s11, s11, s10
	s_lshl_b32 s12, s11, 7
	s_add_u32 s12, s12, 0x7f80000
	s_add_u32 s76, s24, s12
	s_addc_u32 s77, s25, 0
	s_mul_i32 s12, s11, 192
	s_add_u32 s12, s12, 0xd040000
	s_add_u32 s84, s24, s12
	s_addc_u32 s85, s25, 0
	s_mul_i32 s11, s0, 8704
	s_add_u32 s11, s11, s10
	s_lshl_b32 s12, s11, 7
	s_add_u32 s12, s12, 0x9900000
	s_add_u32 s78, s24, s12
	s_addc_u32 s79, s25, 0
	s_lshl_b32 s12, s86, 9
	s_add_u32 s12, s12, 0x11000000
	s_add_u32 s80, s24, s12
	s_addc_u32 s81, s25, 0
	s_lshl_b32 s12, s86, 8
	s_add_u32 s12, s12, 0x12100000
	s_add_u32 s82, s24, s12
	s_addc_u32 s83, s25, 0
	s_waitcnt vmcnt(13)
	v_lshlrev_b32_e32 v0, 16, v0
	v_lshlrev_b32_e32 v1, 16, v1
	v_lshlrev_b32_e32 v2, 16, v2
	v_lshlrev_b32_e32 v3, 16, v3
	v_lshlrev_b32_e32 v4, 16, v4
	v_lshlrev_b32_e32 v5, 16, v5
	v_lshlrev_b32_e32 v6, 16, v6
	v_lshlrev_b32_e32 v7, 16, v7
	v_lshlrev_b32_e32 v10, 16, v8
	v_and_b32_e32 v11, 0xffff0000, v8
	v_lshlrev_b32_e32 v12, 16, v9
	v_and_b32_e32 v13, 0xffff0000, v9
	v_lshlrev_b32_e32 v15, 16, v14
	v_and_b32_e32 v16, 0xffff0000, v14
	v_lshlrev_b32_e32 v17, 16, v17
	v_mul_f32_e32 v22, v0, v0
	v_mul_f32_e32 v23, v1, v1
	v_mul_f32_e32 v24, v2, v2
	v_mul_f32_e32 v25, v3, v3
	v_mul_f32_e32 v26, v4, v4
	v_mul_f32_e32 v27, v5, v5
	v_mul_f32_e32 v28, v6, v6
	v_mul_f32_e32 v29, v7, v7
	v_mul_f32_e32 v30, v10, v10
	v_fmac_f32_e32 v30, v11, v11
	v_fmac_f32_e32 v30, v12, v12
	v_fmac_f32_e32 v30, v13, v13
	v_mul_f32_e32 v31, v15, v15
	v_fmac_f32_e32 v31, v16, v16
	s_waitcnt vmcnt(0)
	v_lshlrev_b32_e32 v40, 16, v40
	v_lshlrev_b32_e32 v41, 16, v41
	v_lshlrev_b32_e32 v42, 16, v42
	v_lshlrev_b32_e32 v43, 16, v43
	v_lshlrev_b32_e32 v44, 16, v44
	v_lshlrev_b32_e32 v45, 16, v45
	v_lshlrev_b32_e32 v46, 16, v46
	v_lshlrev_b32_e32 v47, 16, v47
	v_lshlrev_b32_e32 v50, 16, v48
	v_and_b32_e32 v51, 0xffff0000, v48
	v_lshlrev_b32_e32 v52, 16, v49
	v_and_b32_e32 v53, 0xffff0000, v49
	v_lshlrev_b32_e32 v55, 16, v54
	v_and_b32_e32 v56, 0xffff0000, v54
	v_lshlrev_b32_e32 v57, 16, v57
	v_mul_f32_e32 v62, v40, v40
	v_mul_f32_e32 v63, v41, v41
	v_mul_f32_e32 v64, v42, v42
	v_mul_f32_e32 v65, v43, v43
	v_mul_f32_e32 v66, v44, v44
	v_mul_f32_e32 v67, v45, v45
	v_mul_f32_e32 v68, v46, v46
	v_mul_f32_e32 v69, v47, v47
	v_mul_f32_e32 v70, v50, v50
	v_fmac_f32_e32 v70, v51, v51
	v_fmac_f32_e32 v70, v52, v52
	v_fmac_f32_e32 v70, v53, v53
	v_mul_f32_e32 v71, v55, v55
	v_fmac_f32_e32 v71, v56, v56
	v_add_f32_dpp v22, v22, v22 quad_perm:[1,0,3,2] row_mask:0xf bank_mask:0xf
	v_add_f32_dpp v23, v23, v23 quad_perm:[1,0,3,2] row_mask:0xf bank_mask:0xf
	v_add_f32_dpp v24, v24, v24 quad_perm:[1,0,3,2] row_mask:0xf bank_mask:0xf
	v_add_f32_dpp v25, v25, v25 quad_perm:[1,0,3,2] row_mask:0xf bank_mask:0xf
	v_add_f32_dpp v26, v26, v26 quad_perm:[1,0,3,2] row_mask:0xf bank_mask:0xf
	v_add_f32_dpp v27, v27, v27 quad_perm:[1,0,3,2] row_mask:0xf bank_mask:0xf
	v_add_f32_dpp v28, v28, v28 quad_perm:[1,0,3,2] row_mask:0xf bank_mask:0xf
	v_add_f32_dpp v29, v29, v29 quad_perm:[1,0,3,2] row_mask:0xf bank_mask:0xf
	v_add_f32_dpp v30, v30, v30 quad_perm:[1,0,3,2] row_mask:0xf bank_mask:0xf
	v_add_f32_dpp v31, v31, v31 quad_perm:[1,0,3,2] row_mask:0xf bank_mask:0xf
	v_add_f32_dpp v62, v62, v62 quad_perm:[1,0,3,2] row_mask:0xf bank_mask:0xf
	v_add_f32_dpp v63, v63, v63 quad_perm:[1,0,3,2] row_mask:0xf bank_mask:0xf
	v_add_f32_dpp v64, v64, v64 quad_perm:[1,0,3,2] row_mask:0xf bank_mask:0xf
	v_add_f32_dpp v65, v65, v65 quad_perm:[1,0,3,2] row_mask:0xf bank_mask:0xf
	v_add_f32_dpp v66, v66, v66 quad_perm:[1,0,3,2] row_mask:0xf bank_mask:0xf
	v_add_f32_dpp v67, v67, v67 quad_perm:[1,0,3,2] row_mask:0xf bank_mask:0xf
	v_add_f32_dpp v68, v68, v68 quad_perm:[1,0,3,2] row_mask:0xf bank_mask:0xf
	v_add_f32_dpp v69, v69, v69 quad_perm:[1,0,3,2] row_mask:0xf bank_mask:0xf
	v_add_f32_dpp v70, v70, v70 quad_perm:[1,0,3,2] row_mask:0xf bank_mask:0xf
	v_add_f32_dpp v71, v71, v71 quad_perm:[1,0,3,2] row_mask:0xf bank_mask:0xf
	v_add_f32_dpp v22, v22, v22 quad_perm:[2,3,0,1] row_mask:0xf bank_mask:0xf
	v_add_f32_dpp v23, v23, v23 quad_perm:[2,3,0,1] row_mask:0xf bank_mask:0xf
	v_add_f32_dpp v24, v24, v24 quad_perm:[2,3,0,1] row_mask:0xf bank_mask:0xf
	v_add_f32_dpp v25, v25, v25 quad_perm:[2,3,0,1] row_mask:0xf bank_mask:0xf
	v_add_f32_dpp v26, v26, v26 quad_perm:[2,3,0,1] row_mask:0xf bank_mask:0xf
	v_add_f32_dpp v27, v27, v27 quad_perm:[2,3,0,1] row_mask:0xf bank_mask:0xf
	v_add_f32_dpp v28, v28, v28 quad_perm:[2,3,0,1] row_mask:0xf bank_mask:0xf
	v_add_f32_dpp v29, v29, v29 quad_perm:[2,3,0,1] row_mask:0xf bank_mask:0xf
	v_add_f32_dpp v30, v30, v30 quad_perm:[2,3,0,1] row_mask:0xf bank_mask:0xf
	v_add_f32_dpp v31, v31, v31 quad_perm:[2,3,0,1] row_mask:0xf bank_mask:0xf
	v_add_f32_dpp v62, v62, v62 quad_perm:[2,3,0,1] row_mask:0xf bank_mask:0xf
	v_add_f32_dpp v63, v63, v63 quad_perm:[2,3,0,1] row_mask:0xf bank_mask:0xf
	v_add_f32_dpp v64, v64, v64 quad_perm:[2,3,0,1] row_mask:0xf bank_mask:0xf
	v_add_f32_dpp v65, v65, v65 quad_perm:[2,3,0,1] row_mask:0xf bank_mask:0xf
	v_add_f32_dpp v66, v66, v66 quad_perm:[2,3,0,1] row_mask:0xf bank_mask:0xf
	v_add_f32_dpp v67, v67, v67 quad_perm:[2,3,0,1] row_mask:0xf bank_mask:0xf
	v_add_f32_dpp v68, v68, v68 quad_perm:[2,3,0,1] row_mask:0xf bank_mask:0xf
	v_add_f32_dpp v69, v69, v69 quad_perm:[2,3,0,1] row_mask:0xf bank_mask:0xf
; DI unsigned pack2(float lo, float hi) { f32x2_t v = {lo, hi}; bf16x2_t r = __builtin_convertvector(v, bf16x2_t); return __builtin_bit_cast(unsigned, r); }
; DI bf16_t f2bf(float x) { return (bf16_t)(pack2(x, x) & 0xffffu); }
; DI float bf2f(bf16_t v) { return __uint_as_float(((unsigned)v) << 16); }
; DI float wave_sum(float v) {
; #pragma unroll
;   for (int o = 32; o > 0; o >>= 1) v += __shfl_xor(v, o);
;   return v;
; DI void prep_row_store(const Params& p, int layer, int row, int lane, const PrepRow& R, float gq, float gk, float4 g4, float2 g2) {
;     ...
;   for (int hd = 0; hd < 8; ++hd) {
;     float xv = bf2f(R.hv[hd]);
;     float ss = wave_sum(xv * xv);
;     float y = xv * rsqrtf(ss * (1.0f / 64.f) + 1e-6f) * (hd < 6 ? gq : gk);
;     float pv = __shfl_xor(y, 16);
;     float o = y * cs_c + (upper ? pv : -pv) * cs_s;
;     if (hd < 6) Qg[((size_t)(b * 6 + hd) * NKEY + kp) * 64 + lane] = f2bf(o * qs);
;     else Kg[((size_t)(b * 2 + (hd - 6)) * NKEY + kp) * 64 + lane] = f2bf(o);
;   }
;   {
;     const uint2 w = R.mq;
;     float x0 = bf2f((bf16_t)(w.x & 0xffff)), x1 = bf2f((bf16_t)(w.x >> 16)), x2 = bf2f((bf16_t)(w.y & 0xffff)), x3 = bf2f((bf16_t)(w.y >> 16));
;     float ss = wave_sum(x0 * x0 + x1 * x1 + x2 * x2 + x3 * x3);
;     float rstd = rsqrtf(ss * (1.0f / 256.f) + 1e-6f);
;     uint2 o; o.x = pack2(x0 * rstd * g4.x, x1 * rstd * g4.y); o.y = pack2(x2 * rstd * g4.z, x3 * rstd * g4.w);
;     *(uint2*)(MQN + (size_t)row * 256 + lane * 4) = o;
;   }
;   {
;     const unsigned w = R.mkv;
;     float x0 = bf2f((bf16_t)(w & 0xffff)), x1 = bf2f((bf16_t)(w >> 16));
;     float ss = wave_sum(x0 * x0 + x1 * x1);
	v_add_f32_dpp v70, v70, v70 quad_perm:[2,3,0,1] row_mask:0xf bank_mask:0xf
	v_add_f32_dpp v71, v71, v71 quad_perm:[2,3,0,1] row_mask:0xf bank_mask:0xf
	v_add_f32_dpp v22, v22, v22 row_half_mirror row_mask:0xf bank_mask:0xf
	v_add_f32_dpp v23, v23, v23 row_half_mirror row_mask:0xf bank_mask:0xf
	v_add_f32_dpp v24, v24, v24 row_half_mirror row_mask:0xf bank_mask:0xf
	v_add_f32_dpp v25, v25, v25 row_half_mirror row_mask:0xf bank_mask:0xf
	v_add_f32_dpp v26, v26, v26 row_half_mirror row_mask:0xf bank_mask:0xf
	v_add_f32_dpp v27, v27, v27 row_half_mirror row_mask:0xf bank_mask:0xf
	v_add_f32_dpp v28, v28, v28 row_half_mirror row_mask:0xf bank_mask:0xf
	v_add_f32_dpp v29, v29, v29 row_half_mirror row_mask:0xf bank_mask:0xf
	v_add_f32_dpp v30, v30, v30 row_half_mirror row_mask:0xf bank_mask:0xf
	v_add_f32_dpp v31, v31, v31 row_half_mirror row_mask:0xf bank_mask:0xf
	v_add_f32_dpp v62, v62, v62 row_half_mirror row_mask:0xf bank_mask:0xf
	v_add_f32_dpp v63, v63, v63 row_half_mirror row_mask:0xf bank_mask:0xf
	v_add_f32_dpp v64, v64, v64 row_half_mirror row_mask:0xf bank_mask:0xf
	v_add_f32_dpp v65, v65, v65 row_half_mirror row_mask:0xf bank_mask:0xf
	v_add_f32_dpp v66, v66, v66 row_half_mirror row_mask:0xf bank_mask:0xf
	v_add_f32_dpp v67, v67, v67 row_half_mirror row_mask:0xf bank_mask:0xf
	v_add_f32_dpp v68, v68, v68 row_half_mirror row_mask:0xf bank_mask:0xf
	v_add_f32_dpp v69, v69, v69 row_half_mirror row_mask:0xf bank_mask:0xf
	v_add_f32_dpp v70, v70, v70 row_half_mirror row_mask:0xf bank_mask:0xf
	v_add_f32_dpp v71, v71, v71 row_half_mirror row_mask:0xf bank_mask:0xf
	v_add_f32_dpp v22, v22, v22 row_mirror row_mask:0xf bank_mask:0xf
	v_add_f32_dpp v23, v23, v23 row_mirror row_mask:0xf bank_mask:0xf
	v_add_f32_dpp v24, v24, v24 row_mirror row_mask:0xf bank_mask:0xf
	v_add_f32_dpp v25, v25, v25 row_mirror row_mask:0xf bank_mask:0xf
	v_add_f32_dpp v26, v26, v26 row_mirror row_mask:0xf bank_mask:0xf
	v_add_f32_dpp v27, v27, v27 row_mirror row_mask:0xf bank_mask:0xf
	v_add_f32_dpp v28, v28, v28 row_mirror row_mask:0xf bank_mask:0xf
	v_add_f32_dpp v29, v29, v29 row_mirror row_mask:0xf bank_mask:0xf
	v_add_f32_dpp v30, v30, v30 row_mirror row_mask:0xf bank_mask:0xf
	v_add_f32_dpp v31, v31, v31 row_mirror row_mask:0xf bank_mask:0xf
	v_add_f32_dpp v62, v62, v62 row_mirror row_mask:0xf bank_mask:0xf
	v_add_f32_dpp v63, v63, v63 row_mirror row_mask:0xf bank_mask:0xf
	v_add_f32_dpp v64, v64, v64 row_mirror row_mask:0xf bank_mask:0xf
	v_add_f32_dpp v65, v65, v65 row_mirror row_mask:0xf bank_mask:0xf
	v_add_f32_dpp v66, v66, v66 row_mirror row_mask:0xf bank_mask:0xf
	v_add_f32_dpp v67, v67, v67 row_mirror row_mask:0xf bank_mask:0xf
	v_add_f32_dpp v68, v68, v68 row_mirror row_mask:0xf bank_mask:0xf
	v_add_f32_dpp v69, v69, v69 row_mirror row_mask:0xf bank_mask:0xf
	v_add_f32_dpp v70, v70, v70 row_mirror row_mask:0xf bank_mask:0xf
	v_add_f32_dpp v71, v71, v71 row_mirror row_mask:0xf bank_mask:0xf
	s_nop 1
	v_readlane_b32 s90, v22, 0
	v_readlane_b32 s91, v22, 16
	v_readlane_b32 s55, v22, 32
	v_readlane_b32 s57, v22, 48
	s_nop 1
	v_mov_b32_e32 v22, s90
	v_add_f32_e32 v22, s91, v22
	v_add_f32_e32 v22, s55, v22
	v_add_f32_e32 v22, s57, v22
	v_readlane_b32 s90, v23, 0
	v_readlane_b32 s91, v23, 16
	v_readlane_b32 s55, v23, 32
	v_readlane_b32 s57, v23, 48
	s_nop 1
	v_mov_b32_e32 v23, s90
	v_add_f32_e32 v23, s91, v23
	v_add_f32_e32 v23, s55, v23
	v_add_f32_e32 v23, s57, v23
	v_readlane_b32 s90, v24, 0
	v_readlane_b32 s91, v24, 16
	v_readlane_b32 s55, v24, 32
	v_readlane_b32 s57, v24, 48
	s_nop 1
	v_mov_b32_e32 v24, s90
	v_add_f32_e32 v24, s91, v24
	v_add_f32_e32 v24, s55, v24
	v_add_f32_e32 v24, s57, v24
	v_readlane_b32 s90, v25, 0
	v_readlane_b32 s91, v25, 16
	v_readlane_b32 s55, v25, 32
	v_readlane_b32 s57, v25, 48
	s_nop 1
	v_mov_b32_e32 v25, s90
	v_add_f32_e32 v25, s91, v25
	v_add_f32_e32 v25, s55, v25
	v_add_f32_e32 v25, s57, v25
	v_readlane_b32 s90, v26, 0
	v_readlane_b32 s91, v26, 16
	v_readlane_b32 s55, v26, 32
	v_readlane_b32 s57, v26, 48
	s_nop 1
	v_mov_b32_e32 v26, s90
	v_add_f32_e32 v26, s91, v26
	v_add_f32_e32 v26, s55, v26
	v_add_f32_e32 v26, s57, v26
	v_readlane_b32 s90, v27, 0
	v_readlane_b32 s91, v27, 16
	v_readlane_b32 s55, v27, 32
	v_readlane_b32 s57, v27, 48
	s_nop 1
	v_mov_b32_e32 v27, s90
	v_add_f32_e32 v27, s91, v27
	v_add_f32_e32 v27, s55, v27
	v_add_f32_e32 v27, s57, v27
	v_readlane_b32 s90, v28, 0
	v_readlane_b32 s91, v28, 16
	v_readlane_b32 s55, v28, 32
	v_readlane_b32 s57, v28, 48
	s_nop 1
	v_mov_b32_e32 v28, s90
	v_add_f32_e32 v28, s91, v28
	v_add_f32_e32 v28, s55, v28
	v_add_f32_e32 v28, s57, v28
	v_readlane_b32 s90, v29, 0
	v_readlane_b32 s91, v29, 16
	v_readlane_b32 s55, v29, 32
	v_readlane_b32 s57, v29, 48
	s_nop 1
	v_mov_b32_e32 v29, s90
	v_add_f32_e32 v29, s91, v29
	v_add_f32_e32 v29, s55, v29
	v_add_f32_e32 v29, s57, v29
	v_readlane_b32 s90, v30, 0
	v_readlane_b32 s91, v30, 16
	v_readlane_b32 s55, v30, 32
	v_readlane_b32 s57, v30, 48
	s_nop 1
	v_mov_b32_e32 v30, s90
	v_add_f32_e32 v30, s91, v30
	v_add_f32_e32 v30, s55, v30
	v_add_f32_e32 v30, s57, v30
	v_readlane_b32 s90, v31, 0
	v_readlane_b32 s91, v31, 16
	v_readlane_b32 s55, v31, 32
	v_readlane_b32 s57, v31, 48
	s_nop 1
	v_mov_b32_e32 v31, s90
	v_add_f32_e32 v31, s91, v31
	v_add_f32_e32 v31, s55, v31
	v_add_f32_e32 v31, s57, v31
	v_readlane_b32 s90, v62, 0
	v_readlane_b32 s91, v62, 16
	v_readlane_b32 s55, v62, 32
	v_readlane_b32 s57, v62, 48
	s_nop 1
	v_mov_b32_e32 v62, s90
	v_add_f32_e32 v62, s91, v62
	v_add_f32_e32 v62, s55, v62
	v_add_f32_e32 v62, s57, v62
	v_readlane_b32 s90, v63, 0
	v_readlane_b32 s91, v63, 16
	v_readlane_b32 s55, v63, 32
	v_readlane_b32 s57, v63, 48
; DI unsigned pack2(float lo, float hi) { f32x2_t v = {lo, hi}; bf16x2_t r = __builtin_convertvector(v, bf16x2_t); return __builtin_bit_cast(unsigned, r); }
; DI bf16_t f2bf(float x) { return (bf16_t)(pack2(x, x) & 0xffffu); }
; DI float bf2f(bf16_t v) { return __uint_as_float(((unsigned)v) << 16); }
; DI void prep_row_store(const Params& p, int layer, int row, int lane, const PrepRow& R, float gq, float gk, float4 g4, float2 g2) {
;     ...
;     float xv = bf2f(R.hv[hd]);
;     float ss = wave_sum(xv * xv);
;     float y = xv * rsqrtf(ss * (1.0f / 64.f) + 1e-6f) * (hd < 6 ? gq : gk);
;     float pv = __shfl_xor(y, 16);
;     float o = y * cs_c + (upper ? pv : -pv) * cs_s;
;     if (hd < 6) Qg[((size_t)(b * 6 + hd) * NKEY + kp) * 64 + lane] = f2bf(o * qs);
;     else Kg[((size_t)(b * 2 + (hd - 6)) * NKEY + kp) * 64 + lane] = f2bf(o);
;   }
;   {
;     const uint2 w = R.mq;
;     float x0 = bf2f((bf16_t)(w.x & 0xffff)), x1 = bf2f((bf16_t)(w.x >> 16)), x2 = bf2f((bf16_t)(w.y & 0xffff)), x3 = bf2f((bf16_t)(w.y >> 16));
;     float ss = wave_sum(x0 * x0 + x1 * x1 + x2 * x2 + x3 * x3);
;     float rstd = rsqrtf(ss * (1.0f / 256.f) + 1e-6f);
;     uint2 o; o.x = pack2(x0 * rstd * g4.x, x1 * rstd * g4.y); o.y = pack2(x2 * rstd * g4.z, x3 * rstd * g4.w);
;     *(uint2*)(MQN + (size_t)row * 256 + lane * 4) = o;
;   }
;   {
;     const unsigned w = R.mkv;
;     float x0 = bf2f((bf16_t)(w & 0xffff)), x1 = bf2f((bf16_t)(w >> 16));
;     float ss = wave_sum(x0 * x0 + x1 * x1);
;     float rstd = rsqrtf(ss * (1.0f / 128.f) + 1e-6f);
;     *(unsigned*)(MKVN + (size_t)row * 128 + lane * 2) = pack2(x0 * rstd * g2.x, x1 * rstd * g2.y);
;   }
;   {
;     int d = lane & 31;
;     float xv = bf2f(R.kr);
;     float pv = __shfl_xor(xv, 8);
;     float o = lat ? (xv * tm.x + ((d & 8) ? pv : -pv) * tm.y) : xv;
;     bf16_t ob = f2bf(o);
;     int hb = (lane >> 5) * 3;
; #pragma unroll
;     for (int hh = 0; hh < 3; ++hh) Km[((size_t)(b * 6 + hb + hh) * NKEY + kp) * 96 + 64 + d] = ob;
;   }
	s_nop 1
	v_mov_b32_e32 v63, s90
	v_add_f32_e32 v63, s91, v63
	v_add_f32_e32 v63, s55, v63
	v_add_f32_e32 v63, s57, v63
	v_readlane_b32 s90, v64, 0
	v_readlane_b32 s91, v64, 16
	v_readlane_b32 s55, v64, 32
	v_readlane_b32 s57, v64, 48
	s_nop 1
	v_mov_b32_e32 v64, s90
	v_add_f32_e32 v64, s91, v64
	v_add_f32_e32 v64, s55, v64
	v_add_f32_e32 v64, s57, v64
	v_readlane_b32 s90, v65, 0
	v_readlane_b32 s91, v65, 16
	v_readlane_b32 s55, v65, 32
	v_readlane_b32 s57, v65, 48
	s_nop 1
	v_mov_b32_e32 v65, s90
	v_add_f32_e32 v65, s91, v65
	v_add_f32_e32 v65, s55, v65
	v_add_f32_e32 v65, s57, v65
	v_readlane_b32 s90, v66, 0
	v_readlane_b32 s91, v66, 16
	v_readlane_b32 s55, v66, 32
	v_readlane_b32 s57, v66, 48
	s_nop 1
	v_mov_b32_e32 v66, s90
	v_add_f32_e32 v66, s91, v66
	v_add_f32_e32 v66, s55, v66
	v_add_f32_e32 v66, s57, v66
	v_readlane_b32 s90, v67, 0
	v_readlane_b32 s91, v67, 16
	v_readlane_b32 s55, v67, 32
	v_readlane_b32 s57, v67, 48
	s_nop 1
	v_mov_b32_e32 v67, s90
	v_add_f32_e32 v67, s91, v67
	v_add_f32_e32 v67, s55, v67
	v_add_f32_e32 v67, s57, v67
	v_readlane_b32 s90, v68, 0
	v_readlane_b32 s91, v68, 16
	v_readlane_b32 s55, v68, 32
	v_readlane_b32 s57, v68, 48
	s_nop 1
	v_mov_b32_e32 v68, s90
	v_add_f32_e32 v68, s91, v68
	v_add_f32_e32 v68, s55, v68
	v_add_f32_e32 v68, s57, v68
	v_readlane_b32 s90, v69, 0
	v_readlane_b32 s91, v69, 16
	v_readlane_b32 s55, v69, 32
	v_readlane_b32 s57, v69, 48
	s_nop 1
	v_mov_b32_e32 v69, s90
	v_add_f32_e32 v69, s91, v69
	v_add_f32_e32 v69, s55, v69
	v_add_f32_e32 v69, s57, v69
	v_readlane_b32 s90, v70, 0
	v_readlane_b32 s91, v70, 16
	v_readlane_b32 s55, v70, 32
	v_readlane_b32 s57, v70, 48
	s_nop 1
	v_mov_b32_e32 v70, s90
	v_add_f32_e32 v70, s91, v70
	v_add_f32_e32 v70, s55, v70
	v_add_f32_e32 v70, s57, v70
	v_readlane_b32 s90, v71, 0
	v_readlane_b32 s91, v71, 16
	v_readlane_b32 s55, v71, 32
	v_readlane_b32 s57, v71, 48
	s_nop 1
	v_mov_b32_e32 v71, s90
	v_add_f32_e32 v71, s91, v71
	v_add_f32_e32 v71, s55, v71
	v_add_f32_e32 v71, s57, v71
	s_mov_b32 s0, 0x3c800000
	s_mov_b32 s1, 0x3b800000
	s_mov_b32 s10, 0x3c000000
	v_fma_f32 v22, v22, s0, v161
	v_fma_f32 v23, v23, s0, v161
	v_fma_f32 v24, v24, s0, v161
	v_fma_f32 v25, v25, s0, v161
	v_fma_f32 v26, v26, s0, v161
	v_fma_f32 v27, v27, s0, v161
	v_fma_f32 v28, v28, s0, v161
	v_fma_f32 v29, v29, s0, v161
	v_fma_f32 v30, v30, s1, v161
	v_fma_f32 v31, v31, s10, v161
	v_rsq_f32_e32 v22, v22
	v_rsq_f32_e32 v23, v23
	v_rsq_f32_e32 v24, v24
	v_rsq_f32_e32 v25, v25
	v_rsq_f32_e32 v26, v26
	v_rsq_f32_e32 v27, v27
	v_rsq_f32_e32 v28, v28
	v_rsq_f32_e32 v29, v29
	v_rsq_f32_e32 v30, v30
	v_rsq_f32_e32 v31, v31
	v_fma_f32 v62, v62, s0, v161
	v_fma_f32 v63, v63, s0, v161
	v_fma_f32 v64, v64, s0, v161
	v_fma_f32 v65, v65, s0, v161
	v_fma_f32 v66, v66, s0, v161
	v_fma_f32 v67, v67, s0, v161
	v_fma_f32 v68, v68, s0, v161
	v_fma_f32 v69, v69, s0, v161
	v_fma_f32 v70, v70, s1, v161
	v_fma_f32 v71, v71, s10, v161
	v_rsq_f32_e32 v62, v62
	v_rsq_f32_e32 v63, v63
	v_rsq_f32_e32 v64, v64
	v_rsq_f32_e32 v65, v65
	v_rsq_f32_e32 v66, v66
	v_rsq_f32_e32 v67, v67
	v_rsq_f32_e32 v68, v68
	v_rsq_f32_e32 v69, v69
	v_rsq_f32_e32 v70, v70
	v_rsq_f32_e32 v71, v71
	v_mul_f32_e32 v0, v0, v22
	v_mul_f32_e32 v1, v1, v23
	v_mul_f32_e32 v2, v2, v24
	v_mul_f32_e32 v3, v3, v25
	v_mul_f32_e32 v4, v4, v26
	v_mul_f32_e32 v5, v5, v27
	v_mul_f32_e32 v6, v6, v28
	v_mul_f32_e32 v7, v7, v29
	v_mul_f32_e32 v0, v0, v144
	v_mul_f32_e32 v1, v1, v144
	v_mul_f32_e32 v2, v2, v144
	v_mul_f32_e32 v3, v3, v144
	v_mul_f32_e32 v4, v4, v144
	v_mul_f32_e32 v5, v5, v144
	v_mul_f32_e32 v6, v6, v145
	v_mul_f32_e32 v7, v7, v145
	ds_swizzle_b32 v22, v0 offset:0x401f
	ds_swizzle_b32 v23, v1 offset:0x401f
	ds_swizzle_b32 v24, v2 offset:0x401f
	ds_swizzle_b32 v25, v3 offset:0x401f
	ds_swizzle_b32 v26, v4 offset:0x401f
	ds_swizzle_b32 v27, v5 offset:0x401f
	ds_swizzle_b32 v28, v6 offset:0x401f
	ds_swizzle_b32 v29, v7 offset:0x401f
	v_mul_f32_e32 v40, v40, v62
	v_mul_f32_e32 v41, v41, v63
	v_mul_f32_e32 v42, v42, v64
	v_mul_f32_e32 v43, v43, v65
	v_mul_f32_e32 v44, v44, v66
	v_mul_f32_e32 v45, v45, v67
	v_mul_f32_e32 v46, v46, v68
	v_mul_f32_e32 v47, v47, v69
	v_mul_f32_e32 v40, v40, v144
	v_mul_f32_e32 v41, v41, v144
	v_mul_f32_e32 v42, v42, v144
	v_mul_f32_e32 v43, v43, v144
	v_mul_f32_e32 v44, v44, v144
	v_mul_f32_e32 v45, v45, v144
	v_mul_f32_e32 v46, v46, v145
	v_mul_f32_e32 v47, v47, v145
	ds_swizzle_b32 v62, v40 offset:0x401f
	ds_swizzle_b32 v63, v41 offset:0x401f
	ds_swizzle_b32 v64, v42 offset:0x401f
	ds_swizzle_b32 v65, v43 offset:0x401f
	ds_swizzle_b32 v66, v44 offset:0x401f
	ds_swizzle_b32 v67, v45 offset:0x401f
	ds_swizzle_b32 v68, v46 offset:0x401f
	ds_swizzle_b32 v69, v47 offset:0x401f
	v_mul_f32_e32 v10, v10, v30
	v_mul_f32_e32 v11, v11, v30
	v_mul_f32_e32 v12, v12, v30
	v_mul_f32_e32 v13, v13, v30
	v_mul_f32_e32 v10, v10, v146
	v_mul_f32_e32 v11, v11, v147
	v_mul_f32_e32 v12, v12, v148
	v_mul_f32_e32 v13, v13, v149
	v_cvt_pk_bf16_f32 v8, v10, v11
	v_cvt_pk_bf16_f32 v9, v12, v13
	global_store_dwordx2 v153, v[8:9], s[64:65]
	v_mul_f32_e32 v15, v15, v31
	v_mul_f32_e32 v16, v16, v31
	v_mul_f32_e32 v15, v15, v150
	v_mul_f32_e32 v16, v16, v151
	v_cvt_pk_bf16_f32 v14, v15, v16
	global_store_dword v154, v14, s[66:67]
	v_mov_b32_dpp v32, v17 row_ror:8 row_mask:0xf bank_mask:0xf
	v_mul_f32_e32 v33, v17, v20
	v_xor_b32_e32 v32, v157, v32
	v_fmac_f32_e32 v33, v32, v21
	v_cvt_pk_bf16_f32 v38, v33, v33
	global_store_short v160, v38, s[68:69]
	s_add_u32 s68, s68, 0xcc000
	s_addc_u32 s69, s69, 0
	global_store_short v160, v38, s[68:69]
	s_add_u32 s68, s68, 0xcc000
	s_addc_u32 s69, s69, 0
	global_store_short v160, v38, s[68:69]
	v_mul_f32_e32 v50, v50, v70
	v_mul_f32_e32 v51, v51, v70
	v_mul_f32_e32 v52, v52, v70
	v_mul_f32_e32 v53, v53, v70
	v_mul_f32_e32 v50, v50, v146
	v_mul_f32_e32 v51, v51, v147
	v_mul_f32_e32 v52, v52, v148
	v_mul_f32_e32 v53, v53, v149
	v_cvt_pk_bf16_f32 v48, v50, v51
	v_cvt_pk_bf16_f32 v49, v52, v53
	global_store_dwordx2 v153, v[48:49], s[80:81]
	v_mul_f32_e32 v55, v55, v71
	v_mul_f32_e32 v56, v56, v71
	v_mul_f32_e32 v55, v55, v150
	v_mul_f32_e32 v56, v56, v151
	v_cvt_pk_bf16_f32 v54, v55, v56
	global_store_dword v154, v54, s[82:83]
	v_mov_b32_dpp v72, v57 row_ror:8 row_mask:0xf bank_mask:0xf
	v_mul_f32_e32 v73, v57, v60
	v_xor_b32_e32 v72, v157, v72
	v_fmac_f32_e32 v73, v72, v61
	v_cvt_pk_bf16_f32 v78, v73, v73
	global_store_short v160, v78, s[84:85]
	s_add_u32 s84, s84, 0xcc000
	s_addc_u32 s85, s85, 0
	global_store_short v160, v78, s[84:85]
	s_add_u32 s84, s84, 0xcc000
	s_addc_u32 s85, s85, 0
	global_store_short v160, v78, s[84:85]
	s_waitcnt lgkmcnt(8)
; DI bf16_t f2bf(float x) { return (bf16_t)(pack2(x, x) & 0xffffu); }
; DI float bf2f(bf16_t v) { return __uint_as_float(((unsigned)v) << 16); }
; DI void prep_row_store(const Params& p, int layer, int row, int lane, const PrepRow& R, float gq, float gk, float4 g4, float2 g2) {
;     ...
;   for (int hd = 0; hd < 8; ++hd) {
;     float xv = bf2f(R.hv[hd]);
;     float ss = wave_sum(xv * xv);
;     float y = xv * rsqrtf(ss * (1.0f / 64.f) + 1e-6f) * (hd < 6 ? gq : gk);
;     float pv = __shfl_xor(y, 16);
;     float o = y * cs_c + (upper ? pv : -pv) * cs_s;
;     if (hd < 6) Qg[((size_t)(b * 6 + hd) * NKEY + kp) * 64 + lane] = f2bf(o * qs);
;     else Kg[((size_t)(b * 2 + (hd - 6)) * NKEY + kp) * 64 + lane] = f2bf(o);
;   }
; DI void prep_rows(const Params& p, int layer) {
;     ...
;   for (int pr = gw; pr < (NTOK >> 1); pr += nw) {
;     const int row = pr * 2;
;     PrepRow Ra, Rb;
;     prep_row_load(p, row, U + (size_t)row * INP, lane, Ra);
;     prep_row_load(p, row + 1, U + (size_t)(row + 1) * INP, lane, Rb);
;     prep_row_store(p, layer, row, lane, Ra, gq, gk, g4, g2);
;     prep_row_store(p, layer, row + 1, lane, Rb, gq, gk, g4, g2);
;   }
	v_xor_b32_e32 v22, v156, v22
	v_xor_b32_e32 v23, v156, v23
	v_xor_b32_e32 v24, v156, v24
	v_xor_b32_e32 v25, v156, v25
	v_xor_b32_e32 v26, v156, v26
	v_xor_b32_e32 v27, v156, v27
	v_xor_b32_e32 v28, v156, v28
	v_xor_b32_e32 v29, v156, v29
	v_mul_f32_e32 v0, v0, v18
	v_mul_f32_e32 v1, v1, v18
	v_mul_f32_e32 v2, v2, v18
	v_mul_f32_e32 v3, v3, v18
	v_mul_f32_e32 v4, v4, v18
	v_mul_f32_e32 v5, v5, v18
	v_mul_f32_e32 v6, v6, v18
	v_mul_f32_e32 v7, v7, v18
	v_fmac_f32_e32 v0, v22, v19
	v_fmac_f32_e32 v1, v23, v19
	v_fmac_f32_e32 v2, v24, v19
	v_fmac_f32_e32 v3, v25, v19
	v_fmac_f32_e32 v4, v26, v19
	v_fmac_f32_e32 v5, v27, v19
	v_fmac_f32_e32 v6, v28, v19
	v_fmac_f32_e32 v7, v29, v19
	v_mul_f32_e32 v0, v162, v0
	v_mul_f32_e32 v1, v162, v1
	v_mul_f32_e32 v2, v162, v2
	v_mul_f32_e32 v3, v162, v3
	v_mul_f32_e32 v4, v162, v4
	v_mul_f32_e32 v5, v162, v5
	v_cvt_pk_bf16_f32 v32, v0, v1
	v_cvt_pk_bf16_f32 v33, v2, v3
	v_cvt_pk_bf16_f32 v34, v4, v5
	v_cvt_pk_bf16_f32 v35, v6, v7
	global_store_short v152, v32, s[60:61]
	s_add_u32 s60, s60, 0x88000
	s_addc_u32 s61, s61, 0
	global_store_short_d16_hi v152, v32, s[60:61]
	s_add_u32 s60, s60, 0x88000
	s_addc_u32 s61, s61, 0
	global_store_short v152, v33, s[60:61]
	s_add_u32 s60, s60, 0x88000
	s_addc_u32 s61, s61, 0
	global_store_short_d16_hi v152, v33, s[60:61]
	s_add_u32 s60, s60, 0x88000
	s_addc_u32 s61, s61, 0
	global_store_short v152, v34, s[60:61]
	s_add_u32 s60, s60, 0x88000
	s_addc_u32 s61, s61, 0
	global_store_short_d16_hi v152, v34, s[60:61]
	global_store_short v152, v35, s[62:63]
	s_add_u32 s62, s62, 0x88000
	s_addc_u32 s63, s63, 0
	global_store_short_d16_hi v152, v35, s[62:63]
	s_waitcnt lgkmcnt(0)
	v_xor_b32_e32 v62, v156, v62
	v_xor_b32_e32 v63, v156, v63
	v_xor_b32_e32 v64, v156, v64
	v_xor_b32_e32 v65, v156, v65
	v_xor_b32_e32 v66, v156, v66
	v_xor_b32_e32 v67, v156, v67
	v_xor_b32_e32 v68, v156, v68
	v_xor_b32_e32 v69, v156, v69
	v_mul_f32_e32 v40, v40, v58
	v_mul_f32_e32 v41, v41, v58
	v_mul_f32_e32 v42, v42, v58
	v_mul_f32_e32 v43, v43, v58
	v_mul_f32_e32 v44, v44, v58
	v_mul_f32_e32 v45, v45, v58
	v_mul_f32_e32 v46, v46, v58
	v_mul_f32_e32 v47, v47, v58
	v_fmac_f32_e32 v40, v62, v59
	v_fmac_f32_e32 v41, v63, v59
	v_fmac_f32_e32 v42, v64, v59
	v_fmac_f32_e32 v43, v65, v59
	v_fmac_f32_e32 v44, v66, v59
	v_fmac_f32_e32 v45, v67, v59
	v_fmac_f32_e32 v46, v68, v59
	v_fmac_f32_e32 v47, v69, v59
	v_mul_f32_e32 v40, v162, v40
	v_mul_f32_e32 v41, v162, v41
	v_mul_f32_e32 v42, v162, v42
	v_mul_f32_e32 v43, v162, v43
	v_mul_f32_e32 v44, v162, v44
	v_mul_f32_e32 v45, v162, v45
	v_cvt_pk_bf16_f32 v72, v40, v41
	v_cvt_pk_bf16_f32 v73, v42, v43
	v_cvt_pk_bf16_f32 v74, v44, v45
	v_cvt_pk_bf16_f32 v75, v46, v47
	global_store_short v152, v72, s[76:77]
	s_add_u32 s76, s76, 0x88000
	s_addc_u32 s77, s77, 0
	global_store_short_d16_hi v152, v72, s[76:77]
	s_add_u32 s76, s76, 0x88000
	s_addc_u32 s77, s77, 0
	global_store_short v152, v73, s[76:77]
	s_add_u32 s76, s76, 0x88000
	s_addc_u32 s77, s77, 0
	global_store_short_d16_hi v152, v73, s[76:77]
	s_add_u32 s76, s76, 0x88000
	s_addc_u32 s77, s77, 0
	global_store_short v152, v74, s[76:77]
	s_add_u32 s76, s76, 0x88000
	s_addc_u32 s77, s77, 0
	global_store_short_d16_hi v152, v74, s[76:77]
	global_store_short v152, v75, s[78:79]
	s_add_u32 s78, s78, 0x88000
	s_addc_u32 s79, s79, 0
	global_store_short_d16_hi v152, v75, s[78:79]
	s_add_u32 s53, s53, s54
	s_branch .Lpp_loop_1
.Lpp_done_2:
	v_readlane_b32 s52, v254, 0
	v_readlane_b32 s53, v254, 1
	v_readlane_b32 s54, v254, 2
	v_readlane_b32 s55, v254, 3
	v_readlane_b32 s56, v254, 4
	v_readlane_b32 s57, v254, 5
	v_readlane_b32 s58, v254, 6
	v_readlane_b32 s59, v254, 7
	v_readlane_b32 s60, v254, 8
	v_readlane_b32 s61, v254, 9
	v_readlane_b32 s62, v254, 10
	v_readlane_b32 s63, v254, 11
	v_readlane_b32 s64, v254, 12
	v_readlane_b32 s65, v254, 13
	v_readlane_b32 s66, v254, 14
	v_readlane_b32 s67, v254, 15
	v_readlane_b32 s68, v254, 16
	v_readlane_b32 s69, v254, 17
	v_readlane_b32 s70, v254, 18
	v_readlane_b32 s71, v254, 19
	v_readlane_b32 s72, v254, 20
	v_readlane_b32 s73, v254, 21
	v_readlane_b32 s74, v254, 22
	v_readlane_b32 s75, v254, 23
	v_readlane_b32 s76, v254, 24
	v_readlane_b32 s77, v254, 25
	v_readlane_b32 s78, v254, 26
	v_readlane_b32 s79, v254, 27
	v_readlane_b32 s80, v254, 28
	v_readlane_b32 s81, v254, 29
	v_readlane_b32 s82, v254, 30
	v_readlane_b32 s83, v254, 31
	v_readlane_b32 s84, v254, 32
	v_readlane_b32 s85, v254, 33
	v_readlane_b32 s86, v254, 34
	v_readlane_b32 s87, v254, 35
	v_readlane_b32 s88, v254, 36
	v_readlane_b32 s89, v254, 37
	v_readlane_b32 s90, v254, 38
	v_readlane_b32 s91, v254, 39
	s_nop 3
	s_branch .Lpp_ret
